# v27: GLA pass B epilogue: per-row partial sums added directly (no register shuffles) and the sqrt rescale/class-select logic removed for x = mean-square + eps >= 1e-6 (bit-identical)
# baseline (speedup 1.0000x reference)
; #define LAS __attribute__((address_space(3)))
; __device__ __forceinline__ float bflo(unsigned w) { return __uint_as_float(w << 16); }
; __device__ __forceinline__ float bfhi(unsigned w) { return __uint_as_float(w & 0xffff0000u); }
; __device__ __forceinline__ unsigned pk2(float lo, float hi) { return f2bf(lo) | (f2bf(hi) << 16); }
; template <bool FULL>
; __device__ __forceinline__ void gla_pass(const Params& P, LAS unsigned char* lds, f32x4 (&S)[8][2], int bh, int c0, int L, bool dry) {
;     ...
;         if (FULL) {
;             f32x4 gn[2];
; #pragma unroll
;             for (int vt = 0; vt < 2; ++vt) gn[vt] = *(const f32x4*)(P.gla_norm_g + 32 * w + 4 * g + 16 * vt);
; #pragma unroll
;             for (int tt = 0; tt < 4; ++tt) {
;                 const int t = 16 * tt + fr;
;                 const f32x4 r0 = *(const LAS f32x4*)(red + t * 8), r1 = *(const LAS f32x4*)(red + t * 8 + 4);
;                 const float rstd = 1.0f / sqrtf(((r0[0] + r0[1]) + (r0[2] + r0[3]) + (r1[0] + r1[1]) + (r1[2] + r1[3])) * (1.0f / 256.0f) + RMS_EPS);
; #pragma unroll
;                 for (int vt = 0; vt < 2; ++vt) {
;                     bf16_t* op = (bf16_t*)P.out + (row0 + t) * 2048 + 1024 + h * 256 + 32 * w + 16 * vt + 4 * g;
;                     const u32x2 z = zb[vt][tt]; const f32x4 ov = o[vt][tt] * rstd * gn[vt];
;                     u32x2 r; r.x = pk2(ov[0] * bflo(z.x), ov[1] * bfhi(z.x)); r.y = pk2(ov[2] * bflo(z.y), ov[3] * bfhi(z.y));
;                     if (!dry) *(u32x2*)op = r;
;                 }
;             }
.LBB0_698:
	v_mov_b32_e32 v140, v238
	v_mov_b32_e32 v141, v239
	v_mov_b32_e32 v142, v240
	v_mov_b32_e32 v143, v241
	v_mov_b32_e32 v136, v242
	v_mov_b32_e32 v137, v243
	v_mov_b32_e32 v138, v244
	v_mov_b32_e32 v139, v245
	ds_read_b128 v[208:211], v190
	ds_read_b128 v[212:215], v190 offset:16
	s_waitcnt vmcnt(7)
	v_lshlrev_b32_e32 v217, 16, v181
	v_lshlrev_b32_e32 v216, 16, v180
	v_and_b32_e32 v181, 0xffff0000, v181
	s_waitcnt lgkmcnt(1)
	s_waitcnt lgkmcnt(0)
	v_add_f32_e32 v208, v209, v208
	v_add_f32_e32 v210, v210, v211
	v_add_f32_e32 v214, v214, v215
	v_add_f32_e32 v212, v212, v213
	v_add_f32_e32 v208, v208, v210
	v_add_f32_e32 v208, v208, v212
	v_add_f32_e32 v208, v214, v208
	v_fmamk_f32 v208, v208, 0x3b800000, v202
	v_and_b32_e32 v180, 0xffff0000, v180
	s_waitcnt vmcnt(4)
	v_lshlrev_b32_e32 v219, 16, v179
	v_mov_b32_e32 v210, v208
	v_sqrt_f32_e32 v211, v210
	v_lshlrev_b32_e32 v218, 16, v178
	v_and_b32_e32 v179, 0xffff0000, v179
	v_and_b32_e32 v178, 0xffff0000, v178
	v_add_u32_e32 v212, -1, v211
	v_add_u32_e32 v213, 1, v211
	v_fma_f32 v214, -v212, v211, v210
	v_fma_f32 v215, -v213, v211, v210
	v_cmp_ge_f32_e64 s[8:9], 0, v214
	v_add_u32_e32 v160, s27, v193
	v_lshlrev_b64 v[208:209], 12, v[160:161]
	v_cndmask_b32_e64 v211, v211, v212, s[8:9]
	v_cmp_lt_f32_e64 s[8:9], 0, v215
	v_lshl_add_u64 v[208:209], v[168:169], 0, v[208:209]
	s_add_i32 s27, s27, 64
	v_cndmask_b32_e64 v211, v211, v213, s[8:9]
	s_add_i32 s0, s0, 1
	v_lshl_add_u64 v[170:171], v[170:171], 0, s[14:15]
	v_mov_b32_e32 v210, v211
	v_div_scale_f32 v211, s[8:9], v210, v210, 1.0
	v_rcp_f32_e32 v212, v211
	v_div_scale_f32 v213, vcc, 1.0, v210, 1.0
	s_cmpk_eq_i32 s27, 0x400
	v_fma_f32 v214, -v211, v212, 1.0
	v_fmac_f32_e32 v212, v214, v212
	v_mul_f32_e32 v214, v213, v212
	v_fma_f32 v215, -v211, v214, v213
	v_fmac_f32_e32 v214, v215, v212
	v_fma_f32 v211, -v211, v214, v213
	v_div_fmas_f32 v211, v211, v212, v214
	v_div_fixup_f32 v210, v211, v210, 1.0
	v_pk_mul_f32 v[134:135], v[134:135], v[210:211] op_sel_hi:[1,0]
	v_pk_mul_f32 v[132:133], v[132:133], v[210:211] op_sel_hi:[1,0]
	v_pk_mul_f32 v[130:131], v[130:131], v[210:211] op_sel_hi:[1,0]
	v_pk_mul_f32 v[128:129], v[128:129], v[210:211] op_sel_hi:[1,0]
	v_lshl_add_u64 v[172:173], v[172:173], 0, s[16:17]
	s_waitcnt vmcnt(0)
	v_pk_mul_f32 v[132:133], v[140:141], v[132:133]
	v_pk_mul_f32 v[134:135], v[142:143], v[134:135]
	v_pk_mul_f32 v[128:129], v[136:137], v[128:129]
	v_pk_mul_f32 v[130:131], v[138:139], v[130:131]
	v_mov_b32_e32 v210, v132
	v_mov_b32_e32 v211, v134
	v_mov_b32_e32 v134, v133
	v_mov_b32_e32 v132, v128
	v_mov_b32_e32 v133, v130
	v_mov_b32_e32 v130, v129
	v_pk_mul_f32 v[128:129], v[210:211], v[216:217]
	v_pk_mul_f32 v[134:135], v[134:135], v[180:181]
	v_pk_mul_f32 v[178:179], v[130:131], v[178:179]
	v_cvt_pk_bf16_f32 v128, v128, v134
	v_cvt_pk_bf16_f32 v129, v129, v135
	v_pk_mul_f32 v[132:133], v[132:133], v[218:219]
	global_store_dwordx2 v[208:209], v[128:129], off offset:2048
	ds_read_b128 v[128:131], v205
	v_cvt_pk_bf16_f32 v232, v132, v178
	v_cvt_pk_bf16_f32 v255, v133, v179
	ds_read_b128 v[132:135], v205 offset:16
	s_waitcnt lgkmcnt(1)
	s_waitcnt lgkmcnt(0)
	v_add_f32_e32 v128, v129, v128
	v_add_f32_e32 v130, v130, v131
	v_add_f32_e32 v134, v134, v135
	v_add_f32_e32 v132, v132, v133
	v_add_f32_e32 v128, v128, v130
	v_add_f32_e32 v128, v128, v132
	v_add_f32_e32 v128, v134, v128
	v_fmamk_f32 v128, v128, 0x3b800000, v202
	s_nop 1
	v_sqrt_f32_e32 v129, v128
	s_nop 0
	v_add_u32_e32 v132, -1, v129
	v_fma_f32 v133, -v132, v129, v128
	v_cmp_ge_f32_e64 s[8:9], 0, v133
	v_add_u32_e32 v133, 1, v129
	s_nop 0
	v_cndmask_b32_e64 v132, v129, v132, s[8:9]
	v_fma_f32 v129, -v133, v129, v128
	v_cmp_lt_f32_e64 s[8:9], 0, v129
	s_nop 1
	v_cndmask_b32_e64 v129, v132, v133, s[8:9]
	s_nop 1
	v_mov_b32_e32 v132, v129
	v_div_scale_f32 v133, s[8:9], v132, v132, 1.0
	v_rcp_f32_e32 v134, v133
	v_mov_b32_e32 v129, v255
	v_mov_b32_e32 v128, v232
	global_store_dwordx2 v[208:209], v[128:129], off offset:2080
	v_fma_f32 v128, -v133, v134, 1.0
	v_fmac_f32_e32 v134, v128, v134
	v_div_scale_f32 v128, vcc, 1.0, v132, 1.0
	v_mul_f32_e32 v129, v128, v134
	v_fma_f32 v130, -v133, v129, v128
	v_fmac_f32_e32 v129, v130, v134
	v_fma_f32 v128, -v133, v129, v128
	v_div_fmas_f32 v128, v128, v134, v129
	v_div_fixup_f32 v128, v128, v132, 1.0
	v_pk_mul_f32 v[126:127], v[126:127], v[128:129] op_sel_hi:[1,0]
	v_pk_mul_f32 v[124:125], v[124:125], v[128:129] op_sel_hi:[1,0]
	v_pk_mul_f32 v[126:127], v[142:143], v[126:127]
	v_pk_mul_f32 v[124:125], v[140:141], v[124:125]
	v_lshlrev_b32_e32 v133, 16, v177
	v_lshlrev_b32_e32 v132, 16, v176
	v_mov_b32_e32 v134, v124
	v_mov_b32_e32 v135, v126
	v_pk_mul_f32 v[132:133], v[134:135], v[132:133]
	v_and_b32_e32 v135, 0xffff0000, v177
	v_and_b32_e32 v134, 0xffff0000, v176
	v_mov_b32_e32 v126, v125
	v_pk_mul_f32 v[124:125], v[126:127], v[134:135]
	s_nop 0
	v_and_b32_sdwa v129, v125, v204 dst_sel:DWORD dst_unused:UNUSED_PAD src0_sel:WORD_1 src1_sel:DWORD
	v_cvt_pk_bf16_f32 v124, v132, v124
	v_add_u32_e32 v130, 16, v160
	v_mov_b32_e32 v131, v161
	v_cvt_pk_bf16_f32 v125, v133, v125
	v_lshlrev_b64 v[130:131], 12, v[130:131]
	v_pk_mul_f32 v[122:123], v[122:123], v[128:129] op_sel_hi:[1,0]
	v_pk_mul_f32 v[120:121], v[120:121], v[128:129] op_sel_hi:[1,0]
	v_lshl_add_u64 v[130:131], v[168:169], 0, v[130:131]
	v_pk_mul_f32 v[120:121], v[136:137], v[120:121]
	v_pk_mul_f32 v[122:123], v[138:139], v[122:123]
	global_store_dwordx2 v[130:131], v[124:125], off offset:2048
	v_lshlrev_b32_e32 v125, 16, v175
	v_lshlrev_b32_e32 v124, 16, v174
	v_mov_b32_e32 v126, v120
	v_mov_b32_e32 v127, v122
	v_pk_mul_f32 v[124:125], v[126:127], v[124:125]
	v_and_b32_e32 v127, 0xffff0000, v175
	v_and_b32_e32 v126, 0xffff0000, v174
	v_mov_b32_e32 v122, v121
	v_pk_mul_f32 v[128:129], v[122:123], v[126:127]
	ds_read_b128 v[120:123], v206
	v_cvt_pk_bf16_f32 v237, v124, v128
	v_cvt_pk_bf16_f32 v235, v125, v129
	ds_read_b128 v[124:127], v206 offset:16
	s_waitcnt lgkmcnt(1)
; #define LAS __attribute__((address_space(3)))
; __device__ __forceinline__ float bflo(unsigned w) { return __uint_as_float(w << 16); }
; __device__ __forceinline__ float bfhi(unsigned w) { return __uint_as_float(w & 0xffff0000u); }
; __device__ __forceinline__ unsigned pk2(float lo, float hi) { return f2bf(lo) | (f2bf(hi) << 16); }
; template <bool FULL>
; __device__ __forceinline__ void gla_pass(const Params& P, LAS unsigned char* lds, f32x4 (&S)[8][2], int bh, int c0, int L, bool dry) {
;     ...
;         if (FULL) {
;             f32x4 gn[2];
; #pragma unroll
;             for (int vt = 0; vt < 2; ++vt) gn[vt] = *(const f32x4*)(P.gla_norm_g + 32 * w + 4 * g + 16 * vt);
; #pragma unroll
;             for (int tt = 0; tt < 4; ++tt) {
;                 const int t = 16 * tt + fr;
;                 const f32x4 r0 = *(const LAS f32x4*)(red + t * 8), r1 = *(const LAS f32x4*)(red + t * 8 + 4);
;                 const float rstd = 1.0f / sqrtf(((r0[0] + r0[1]) + (r0[2] + r0[3]) + (r1[0] + r1[1]) + (r1[2] + r1[3])) * (1.0f / 256.0f) + RMS_EPS);
; #pragma unroll
;                 for (int vt = 0; vt < 2; ++vt) {
;                     bf16_t* op = (bf16_t*)P.out + (row0 + t) * 2048 + 1024 + h * 256 + 32 * w + 16 * vt + 4 * g;
;                     const u32x2 z = zb[vt][tt]; const f32x4 ov = o[vt][tt] * rstd * gn[vt];
;                     u32x2 r; r.x = pk2(ov[0] * bflo(z.x), ov[1] * bfhi(z.x)); r.y = pk2(ov[2] * bflo(z.y), ov[3] * bfhi(z.y));
;                     if (!dry) *(u32x2*)op = r;
;                 }
;             }
	s_waitcnt lgkmcnt(0)
	v_add_f32_e32 v120, v121, v120
	v_add_f32_e32 v122, v122, v123
	v_add_f32_e32 v126, v126, v127
	v_add_f32_e32 v124, v124, v125
	v_add_f32_e32 v120, v120, v122
	v_add_f32_e32 v120, v120, v124
	v_add_f32_e32 v120, v126, v120
	v_fmamk_f32 v120, v120, 0x3b800000, v202
	s_nop 1
	v_sqrt_f32_e32 v121, v120
	s_nop 0
	v_add_u32_e32 v124, -1, v121
	v_fma_f32 v125, -v124, v121, v120
	v_cmp_ge_f32_e64 s[8:9], 0, v125
	v_add_u32_e32 v125, 1, v121
	s_nop 0
	v_cndmask_b32_e64 v124, v121, v124, s[8:9]
	v_fma_f32 v121, -v125, v121, v120
	v_cmp_lt_f32_e64 s[8:9], 0, v121
	s_nop 1
	v_cndmask_b32_e64 v121, v124, v125, s[8:9]
	s_nop 1
	v_mov_b32_e32 v124, v121
	v_div_scale_f32 v125, s[8:9], v124, v124, 1.0
	v_rcp_f32_e32 v126, v125
	v_mov_b32_e32 v121, v235
	v_mov_b32_e32 v120, v237
	global_store_dwordx2 v[130:131], v[120:121], off offset:2080
	v_fma_f32 v120, -v125, v126, 1.0
	v_fmac_f32_e32 v126, v120, v126
	v_div_scale_f32 v120, vcc, 1.0, v124, 1.0
	v_mul_f32_e32 v121, v120, v126
	v_fma_f32 v122, -v125, v121, v120
	v_fmac_f32_e32 v121, v122, v126
	v_fma_f32 v120, -v125, v121, v120
	v_div_fmas_f32 v120, v120, v126, v121
	v_div_fixup_f32 v120, v120, v124, 1.0
	v_pk_mul_f32 v[110:111], v[110:111], v[120:121] op_sel_hi:[1,0]
	v_pk_mul_f32 v[108:109], v[108:109], v[120:121] op_sel_hi:[1,0]
	v_pk_mul_f32 v[110:111], v[142:143], v[110:111]
	v_pk_mul_f32 v[108:109], v[140:141], v[108:109]
	v_lshlrev_b32_e32 v125, 16, v151
	v_lshlrev_b32_e32 v124, 16, v150
	v_mov_b32_e32 v126, v108
	v_mov_b32_e32 v127, v110
	v_pk_mul_f32 v[124:125], v[126:127], v[124:125]
	v_and_b32_e32 v127, 0xffff0000, v151
	v_and_b32_e32 v126, 0xffff0000, v150
	v_mov_b32_e32 v110, v109
	v_pk_mul_f32 v[108:109], v[110:111], v[126:127]
	s_nop 0
	v_and_b32_sdwa v121, v109, v204 dst_sel:DWORD dst_unused:UNUSED_PAD src0_sel:WORD_1 src1_sel:DWORD
	v_cvt_pk_bf16_f32 v108, v124, v108
	v_add_u32_e32 v122, 32, v160
	v_mov_b32_e32 v123, v161
	v_cvt_pk_bf16_f32 v109, v125, v109
	v_lshlrev_b64 v[122:123], 12, v[122:123]
	v_pk_mul_f32 v[106:107], v[106:107], v[120:121] op_sel_hi:[1,0]
	v_pk_mul_f32 v[104:105], v[104:105], v[120:121] op_sel_hi:[1,0]
	v_lshl_add_u64 v[122:123], v[168:169], 0, v[122:123]
	v_pk_mul_f32 v[104:105], v[136:137], v[104:105]
	v_pk_mul_f32 v[106:107], v[138:139], v[106:107]
	global_store_dwordx2 v[122:123], v[108:109], off offset:2048
	v_lshlrev_b32_e32 v109, 16, v149
	v_lshlrev_b32_e32 v108, 16, v148
	v_mov_b32_e32 v110, v104
	v_mov_b32_e32 v111, v106
	v_pk_mul_f32 v[108:109], v[110:111], v[108:109]
	v_and_b32_e32 v111, 0xffff0000, v149
	v_and_b32_e32 v110, 0xffff0000, v148
	v_mov_b32_e32 v106, v105
	v_pk_mul_f32 v[120:121], v[106:107], v[110:111]
	ds_read_b128 v[104:107], v207
	v_cvt_pk_bf16_f32 v255, v108, v120
	v_cvt_pk_bf16_f32 v254, v109, v121
	ds_read_b128 v[108:111], v207 offset:16
	s_waitcnt lgkmcnt(1)
	s_waitcnt lgkmcnt(0)
	v_add_f32_e32 v104, v105, v104
	v_add_f32_e32 v106, v106, v107
	v_add_f32_e32 v110, v110, v111
	v_add_f32_e32 v108, v108, v109
	v_add_f32_e32 v104, v104, v106
	v_add_f32_e32 v104, v104, v108
	v_add_f32_e32 v104, v110, v104
	v_fmamk_f32 v104, v104, 0x3b800000, v202
	s_nop 1
	v_sqrt_f32_e32 v105, v104
	v_add_u32_e32 v160, 48, v160
	v_add_u32_e32 v108, -1, v105
	v_fma_f32 v109, -v108, v105, v104
	v_cmp_ge_f32_e64 s[8:9], 0, v109
	v_add_u32_e32 v109, 1, v105
	s_nop 0
	v_cndmask_b32_e64 v108, v105, v108, s[8:9]
	v_fma_f32 v105, -v109, v105, v104
	v_cmp_lt_f32_e64 s[8:9], 0, v105
	s_nop 1
	v_cndmask_b32_e64 v105, v108, v109, s[8:9]
	s_nop 1
	v_mov_b32_e32 v108, v105
	v_div_scale_f32 v109, s[8:9], v108, v108, 1.0
	v_rcp_f32_e32 v110, v109
	v_mov_b32_e32 v105, v254
	v_mov_b32_e32 v104, v255
	global_store_dwordx2 v[122:123], v[104:105], off offset:2080
	v_fma_f32 v104, -v109, v110, 1.0
	v_fmac_f32_e32 v110, v104, v110
	v_div_scale_f32 v104, vcc, 1.0, v108, 1.0
	v_mul_f32_e32 v105, v104, v110
	v_fma_f32 v106, -v109, v105, v104
	v_fmac_f32_e32 v105, v106, v110
	v_fma_f32 v104, -v109, v105, v104
	v_div_fmas_f32 v104, v104, v110, v105
	v_div_fixup_f32 v104, v104, v108, 1.0
	v_pk_mul_f32 v[108:109], v[118:119], v[104:105] op_sel_hi:[1,0]
	v_pk_mul_f32 v[110:111], v[116:117], v[104:105] op_sel_hi:[1,0]
	v_pk_mul_f32 v[108:109], v[142:143], v[108:109]
	v_pk_mul_f32 v[110:111], v[140:141], v[110:111]
	v_lshlrev_b32_e32 v117, 16, v147
	v_lshlrev_b32_e32 v116, 16, v146
	v_mov_b32_e32 v118, v110
	v_mov_b32_e32 v119, v108
	v_pk_mul_f32 v[116:117], v[118:119], v[116:117]
	v_and_b32_e32 v119, 0xffff0000, v147
	v_and_b32_e32 v118, 0xffff0000, v146
	v_mov_b32_e32 v108, v111
	v_pk_mul_f32 v[108:109], v[108:109], v[118:119]
	s_nop 0
	v_cvt_pk_bf16_f32 v108, v116, v108
	v_and_b32_sdwa v105, v117, v204 dst_sel:DWORD dst_unused:UNUSED_PAD src0_sel:WORD_1 src1_sel:DWORD
	v_cvt_pk_bf16_f32 v109, v117, v109
	v_lshlrev_b64 v[106:107], 12, v[160:161]
	v_add3_u32 v105, v117, v105, s1
	v_lshl_add_u64 v[106:107], v[168:169], 0, v[106:107]
	global_store_dwordx2 v[106:107], v[108:109], off offset:2048
	v_pk_mul_f32 v[108:109], v[114:115], v[104:105] op_sel_hi:[1,0]
	v_pk_mul_f32 v[104:105], v[112:113], v[104:105] op_sel_hi:[1,0]
	v_pk_mul_f32 v[108:109], v[138:139], v[108:109]
	v_pk_mul_f32 v[104:105], v[136:137], v[104:105]
	v_lshlrev_b32_e32 v111, 16, v145
	v_lshlrev_b32_e32 v110, 16, v144
	v_mov_b32_e32 v112, v104
	v_mov_b32_e32 v113, v108
	v_pk_mul_f32 v[110:111], v[112:113], v[110:111]
	v_and_b32_e32 v113, 0xffff0000, v145
	v_and_b32_e32 v112, 0xffff0000, v144
	v_mov_b32_e32 v108, v105
	v_pk_mul_f32 v[104:105], v[108:109], v[112:113]
	s_nop 0
	v_cvt_pk_bf16_f32 v104, v110, v104
	v_cvt_pk_bf16_f32 v105, v111, v105
	global_store_dwordx2 v[106:107], v[104:105], off offset:2080
	s_barrier
	s_cbranch_scc1 .LBB0_714
